# slot conversion with the original 8-loads-in-flight item loop (no unroll), U0=13312
# baseline (speedup 1.0000x reference)
.LBB0_34:
	v_lshl_add_u64 v[36:37], v[20:21], 0, s[20:21]
	v_lshl_add_u64 v[38:39], v[18:19], 0, s[20:21]
	v_lshl_add_u64 v[40:41], v[16:17], 0, s[20:21]
	v_lshl_add_u64 v[42:43], v[14:15], 0, s[20:21]
	v_lshl_add_u64 v[44:45], v[12:13], 0, s[20:21]
	v_lshl_add_u64 v[46:47], v[10:11], 0, s[20:21]
	v_lshl_add_u64 v[48:49], v[8:9], 0, s[20:21]
	v_lshl_add_u64 v[50:51], v[6:7], 0, s[20:21]
	global_load_dword v52, v[36:37], off nt
	global_load_dword v53, v[38:39], off nt
	global_load_dword v54, v[40:41], off nt
	global_load_dword v55, v[42:43], off nt
	global_load_dword v56, v[44:45], off nt
	global_load_dword v57, v[46:47], off nt
	global_load_dword v58, v[48:49], off nt
	global_load_dword v59, v[50:51], off nt
	s_add_u32 s20, s20, 0x8000
	s_addc_u32 s21, s21, 0
	v_add_u32_e32 v36, 0x400, v35
	s_cmp_lg_u32 s20, 0x20000
	s_waitcnt vmcnt(6)
	ds_write2_b32 v35, v52, v53 offset1:66
	s_waitcnt vmcnt(4)
	ds_write2_b32 v35, v54, v55 offset0:132 offset1:198
	s_waitcnt vmcnt(2)
	ds_write2_b32 v36, v56, v57 offset0:8 offset1:74
	s_waitcnt vmcnt(0)
	ds_write2_b32 v36, v58, v59 offset0:140 offset1:206
	v_add_u32_e32 v35, 0x840, v35
	s_cbranch_scc1 .LBB0_34
	s_waitcnt lgkmcnt(0)
	s_lshl_b32 s20, s22, 5
	ds_read2_b32 v[10:11], v23 offset1:8
	s_and_b32 s33, s20, 0x1e0
	s_lshl_b32 s20, s23, 1
	ds_read2_b32 v[14:15], v23 offset0:33 offset1:41
	s_add_u32 s20, s30, s20
	s_addc_u32 s21, s31, 0
	ds_read2_b32 v[16:17], v23 offset0:66 offset1:74
	v_lshl_add_u64 v[6:7], s[20:21], 0, v[2:3]
	ds_read2_b32 v[18:19], v23 offset0:99 offset1:107
	v_lshl_add_u64 v[12:13], v[6:7], 0, s[38:39]
	s_waitcnt lgkmcnt(3)
	v_bfe_u32 v6, v10, 16, 1
	v_add3_u32 v6, v10, v6, s26
	s_waitcnt lgkmcnt(2)
	v_bfe_u32 v7, v14, 16, 1
	ds_read2_b32 v[20:21], v23 offset0:132 offset1:140
	v_lshrrev_b32_e32 v6, 16, v6
	v_add3_u32 v7, v14, v7, s26
	ds_read2_b32 v[36:37], v23 offset0:165 offset1:173
	v_and_or_b32 v6, v7, s27, v6
	s_waitcnt lgkmcnt(3)
	v_bfe_u32 v7, v16, 16, 1
	v_add3_u32 v7, v16, v7, s26
	s_waitcnt lgkmcnt(2)
	v_bfe_u32 v8, v18, 16, 1
	ds_read2_b32 v[38:39], v23 offset0:198 offset1:206
	v_lshrrev_b32_e32 v7, 16, v7
	v_add3_u32 v8, v18, v8, s26
	ds_read2_b32 v[40:41], v23 offset0:231 offset1:239
	v_and_or_b32 v7, v8, s27, v7
	s_waitcnt lgkmcnt(3)
	v_bfe_u32 v8, v20, 16, 1
	v_add3_u32 v8, v20, v8, s26
	s_waitcnt lgkmcnt(2)
	v_bfe_u32 v9, v36, 16, 1
	v_lshrrev_b32_e32 v8, 16, v8
	v_add3_u32 v9, v36, v9, s26
	v_and_or_b32 v8, v9, s27, v8
	s_waitcnt lgkmcnt(1)
	v_bfe_u32 v9, v38, 16, 1
	v_add3_u32 v9, v38, v9, s26
	s_waitcnt lgkmcnt(0)
	v_bfe_u32 v10, v40, 16, 1
	v_lshrrev_b32_e32 v9, 16, v9
	v_add3_u32 v10, v40, v10, s26
	v_and_or_b32 v9, v10, s27, v9
	v_or_b32_e32 v10, s33, v22
	v_lshlrev_b32_e32 v42, 10, v10
	v_mov_b32_e32 v43, v3
	v_lshl_add_u64 v[42:43], v[12:13], 0, v[42:43]
	global_store_dwordx4 v[42:43], v[6:9], off
	v_bfe_u32 v10, v41, 16, 1
	v_add3_u32 v10, v41, v10, s26
	v_bfe_u32 v6, v11, 16, 1
	v_add3_u32 v6, v11, v6, s26
	v_bfe_u32 v7, v15, 16, 1
	v_lshrrev_b32_e32 v6, 16, v6
	v_add3_u32 v7, v15, v7, s26
	v_and_or_b32 v6, v7, s27, v6
	v_bfe_u32 v7, v17, 16, 1
	v_add3_u32 v7, v17, v7, s26
	v_bfe_u32 v8, v19, 16, 1
	v_lshrrev_b32_e32 v7, 16, v7
	v_add3_u32 v8, v19, v8, s26
	v_and_or_b32 v7, v8, s27, v7
	v_bfe_u32 v8, v21, 16, 1
	v_add3_u32 v8, v21, v8, s26
	v_bfe_u32 v9, v37, 16, 1
	v_lshrrev_b32_e32 v8, 16, v8
	v_add3_u32 v9, v37, v9, s26
	v_and_or_b32 v8, v9, s27, v8
	v_bfe_u32 v9, v39, 16, 1
	v_add3_u32 v9, v39, v9, s26
	v_lshrrev_b32_e32 v9, 16, v9
	v_and_or_b32 v9, v10, s27, v9
	v_or_b32_e32 v10, s33, v24
	v_lshlrev_b32_e32 v10, 10, v10
	v_mov_b32_e32 v11, v3
	ds_read2_b32 v[14:15], v23 offset0:16 offset1:24
	v_lshl_add_u64 v[10:11], v[12:13], 0, v[10:11]
	global_store_dwordx4 v[10:11], v[6:9], off
	ds_read2_b32 v[10:11], v23 offset0:49 offset1:57
	ds_read2_b32 v[16:17], v23 offset0:82 offset1:90
	ds_read2_b32 v[18:19], v23 offset0:115 offset1:123
	s_waitcnt lgkmcnt(3)
	v_bfe_u32 v6, v14, 16, 1
	v_add3_u32 v6, v14, v6, s26
	s_waitcnt lgkmcnt(2)
	v_bfe_u32 v7, v10, 16, 1
	ds_read2_b32 v[20:21], v23 offset0:148 offset1:156
	v_lshrrev_b32_e32 v6, 16, v6
	v_add3_u32 v7, v10, v7, s26
	ds_read2_b32 v[36:37], v23 offset0:181 offset1:189
	v_and_or_b32 v6, v7, s27, v6
	s_waitcnt lgkmcnt(3)
	v_bfe_u32 v7, v16, 16, 1
	v_add3_u32 v7, v16, v7, s26
	s_waitcnt lgkmcnt(2)
	v_bfe_u32 v8, v18, 16, 1
	ds_read2_b32 v[38:39], v23 offset0:214 offset1:222
	v_lshrrev_b32_e32 v7, 16, v7
	v_add3_u32 v8, v18, v8, s26
	ds_read2_b32 v[40:41], v23 offset0:247 offset1:255
	v_and_or_b32 v7, v8, s27, v7
	s_waitcnt lgkmcnt(3)
	v_bfe_u32 v8, v20, 16, 1
	v_add3_u32 v8, v20, v8, s26
	s_waitcnt lgkmcnt(2)
	v_bfe_u32 v9, v36, 16, 1
	v_lshrrev_b32_e32 v8, 16, v8
	v_add3_u32 v9, v36, v9, s26
	v_and_or_b32 v8, v9, s27, v8
	s_waitcnt lgkmcnt(1)
	v_bfe_u32 v9, v38, 16, 1
	v_add3_u32 v9, v38, v9, s26
	s_waitcnt lgkmcnt(0)
	v_bfe_u32 v10, v40, 16, 1
	v_lshrrev_b32_e32 v9, 16, v9
	v_add3_u32 v10, v40, v10, s26
	v_and_or_b32 v9, v10, s27, v9
	v_or_b32_e32 v10, s33, v25
	v_lshlrev_b32_e32 v42, 10, v10
	v_mov_b32_e32 v43, v3
	v_lshl_add_u64 v[42:43], v[12:13], 0, v[42:43]
	global_store_dwordx4 v[42:43], v[6:9], off
	v_bfe_u32 v10, v41, 16, 1
	v_add3_u32 v10, v41, v10, s26
	v_bfe_u32 v6, v15, 16, 1
	v_add3_u32 v6, v15, v6, s26
	v_bfe_u32 v7, v11, 16, 1
	v_lshrrev_b32_e32 v6, 16, v6
	v_add3_u32 v7, v11, v7, s26
	v_and_or_b32 v6, v7, s27, v6
	v_bfe_u32 v7, v17, 16, 1
	v_add3_u32 v7, v17, v7, s26
	v_bfe_u32 v8, v19, 16, 1
	v_lshrrev_b32_e32 v7, 16, v7
	v_add3_u32 v8, v19, v8, s26
	v_and_or_b32 v7, v8, s27, v7
	v_bfe_u32 v8, v21, 16, 1
	v_add3_u32 v8, v21, v8, s26
	v_bfe_u32 v9, v37, 16, 1
	v_lshrrev_b32_e32 v8, 16, v8
	v_add3_u32 v9, v37, v9, s26
	v_and_or_b32 v8, v9, s27, v8
	v_bfe_u32 v9, v39, 16, 1
	v_add3_u32 v9, v39, v9, s26
	v_lshrrev_b32_e32 v9, 16, v9
	v_and_or_b32 v9, v10, s27, v9
	v_or_b32_e32 v10, s33, v26
	v_lshlrev_b32_e32 v10, 10, v10
	v_mov_b32_e32 v11, v3
	v_lshl_add_u64 v[10:11], v[12:13], 0, v[10:11]
	global_store_dwordx4 v[10:11], v[6:9], off
	s_waitcnt lgkmcnt(0)
